# attention PV sections (dk=64 and dk=192): exp/row-sum/pack work of the next key slice and the V reads two slices ahead interleaved after every single PV MFMA instead of after each group of four
# baseline (speedup 1.0000x reference)
; DI unsigned cvt_pk_bf16(float lo, float hi) { unsigned r; asm volatile("v_cvt_pk_bf16_f32 %0, %1, %2" : "=v"(r) : "v"(lo), "v"(hi)); return r; }
; template <int DK>
; DI void attn_pass(const AttnSrc& s, const int q0, const float sc, LAS unsigned char* lds, f32x16 (&O)[4]) {
;     ...
;         for (int j = 0; j < 16; ++j) { p0[j] = __builtin_amdgcn_exp2f(p0[j]); p1[j] = __builtin_amdgcn_exp2f(p1[j]); rs += p0[j] + p1[j]; }
;       } else {
;         const float cand = mx * sc;
;         const bool grow = cand > mrun + 8.f;
;         if (__builtin_amdgcn_ballot_w64(grow) != 0ull) {
;           const float mnew = grow ? cand : mrun;
;           const float alpha = __builtin_amdgcn_exp2f(mrun - mnew);
;           mrun = mnew; lrun *= alpha;
; #pragma unroll
;           for (int i = 0; i < 4; ++i)
; #pragma unroll
;             for (int j = 0; j < 16; ++j) O[i][j] *= alpha;
;         }
; #pragma unroll
;         for (int j = 0; j < 16; ++j) { p0[j] = __builtin_amdgcn_exp2f(p0[j] * sc - mrun); p1[j] = __builtin_amdgcn_exp2f(p1[j] * sc - mrun); rs += p0[j] + p1[j]; }
;       }
;       lrun += rs;
;       bf16x8 pb[4];
;       { u32x4 w;
;         w.x = cvt_pk_bf16(p0[0], p0[1]); w.y = cvt_pk_bf16(p0[2], p0[3]); w.z = cvt_pk_bf16(p0[4], p0[5]); w.w = cvt_pk_bf16(p0[6], p0[7]); pb[0] = __builtin_bit_cast(bf16x8, w);
;         w.x = cvt_pk_bf16(p0[8], p0[9]); w.y = cvt_pk_bf16(p0[10], p0[11]); w.z = cvt_pk_bf16(p0[12], p0[13]); w.w = cvt_pk_bf16(p0[14], p0[15]); pb[1] = __builtin_bit_cast(bf16x8, w);
;         w.x = cvt_pk_bf16(p1[0], p1[1]); w.y = cvt_pk_bf16(p1[2], p1[3]); w.z = cvt_pk_bf16(p1[4], p1[5]); w.w = cvt_pk_bf16(p1[6], p1[7]); pb[2] = __builtin_bit_cast(bf16x8, w);
;         w.x = cvt_pk_bf16(p1[8], p1[9]); w.y = cvt_pk_bf16(p1[10], p1[11]); w.z = cvt_pk_bf16(p1[12], p1[13]); w.w = cvt_pk_bf16(p1[14], p1[15]); pb[3] = __builtin_bit_cast(bf16x8, w); }
; #pragma unroll
;       for (int vt = 0; vt < 4; ++vt) {
;         if (vt + 1 < 4) vload(vt + 1, (vt + 1) & 1);
;         __builtin_amdgcn_s_setprio(1);
; #pragma unroll
;         for (int ks = 0; ks < 4; ++ks) O[vt] = __builtin_amdgcn_mfma_f32_32x32x16_bf16(vf[vt & 1][ks], pb[ks], O[vt], 0, 0, 0);
;         __builtin_amdgcn_s_setprio(0);
;       }
.Ln64_exp:
	v_exp_f32_e32 v112, v112
	v_exp_f32_e32 v113, v113
	v_exp_f32_e32 v114, v114
	v_exp_f32_e32 v115, v115
	v_exp_f32_e32 v116, v116
	v_exp_f32_e32 v117, v117
	v_exp_f32_e32 v118, v118
	v_exp_f32_e32 v119, v119
	v_add_f32_e32 v0, v112, v113
	v_add_f32_e32 v15, v114, v115
	v_add_f32_e32 v0, v0, v116
	v_add_f32_e32 v15, v15, v117
	v_add_f32_e32 v0, v0, v118
	v_add_f32_e32 v15, v15, v119
	v_cvt_pk_bf16_f32 v112, v112, v113
	v_cvt_pk_bf16_f32 v113, v114, v115
	v_cvt_pk_bf16_f32 v114, v116, v117
	v_cvt_pk_bf16_f32 v115, v118, v119
	ds_read_b64_tr_b16 v[230:231], v246 offset:12288
	ds_read_b64_tr_b16 v[232:233], v246 offset:14336
	ds_read_b64_tr_b16 v[234:235], v247 offset:12288
	ds_read_b64_tr_b16 v[236:237], v247 offset:14336
	ds_read_b64_tr_b16 v[238:239], v248 offset:12288
	ds_read_b64_tr_b16 v[240:241], v248 offset:14336
	ds_read_b64_tr_b16 v[242:243], v249 offset:12288
	ds_read_b64_tr_b16 v[244:245], v249 offset:14336
	s_setprio 1
	s_waitcnt lgkmcnt(14)
	v_mfma_f32_32x32x16_bf16 v[64:79], v[2:5], v[112:115], v[64:79]
	v_exp_f32_e32 v120, v120
	v_exp_f32_e32 v121, v121
	v_add_f32_e32 v0, v0, v120
	v_add_f32_e32 v15, v15, v121
	v_cvt_pk_bf16_f32 v116, v120, v121
	ds_read_b64_tr_b16 v[2:3], v246 offset:16384
	ds_read_b64_tr_b16 v[4:5], v246 offset:18432
	s_waitcnt lgkmcnt(14)
	v_mfma_f32_32x32x16_bf16 v[48:63], v[6:9], v[112:115], v[48:63]
	v_exp_f32_e32 v122, v122
	v_exp_f32_e32 v123, v123
	v_add_f32_e32 v0, v0, v122
	v_add_f32_e32 v15, v15, v123
	v_cvt_pk_bf16_f32 v117, v122, v123
	ds_read_b64_tr_b16 v[6:7], v247 offset:16384
	ds_read_b64_tr_b16 v[8:9], v247 offset:18432
	s_waitcnt lgkmcnt(14)
	v_mfma_f32_32x32x16_bf16 v[32:47], v[10:13], v[112:115], v[32:47]
	v_exp_f32_e32 v124, v124
	v_exp_f32_e32 v125, v125
	v_add_f32_e32 v0, v0, v124
	v_add_f32_e32 v15, v15, v125
	v_cvt_pk_bf16_f32 v118, v124, v125
	ds_read_b64_tr_b16 v[10:11], v248 offset:16384
	ds_read_b64_tr_b16 v[12:13], v248 offset:18432
	s_waitcnt lgkmcnt(14)
	v_mfma_f32_32x32x16_bf16 v[16:31], v[144:147], v[112:115], v[16:31]
	v_exp_f32_e32 v126, v126
	v_exp_f32_e32 v127, v127
	v_add_f32_e32 v0, v0, v126
	v_add_f32_e32 v15, v15, v127
	v_cvt_pk_bf16_f32 v119, v126, v127
	ds_read_b64_tr_b16 v[144:145], v249 offset:16384
	ds_read_b64_tr_b16 v[146:147], v249 offset:18432
	s_waitcnt lgkmcnt(14)
	v_mfma_f32_32x32x16_bf16 v[64:79], v[230:233], v[116:119], v[64:79]
	v_exp_f32_e32 v96, v96
	v_exp_f32_e32 v97, v97
	v_add_f32_e32 v0, v0, v96
	v_add_f32_e32 v15, v15, v97
	v_cvt_pk_bf16_f32 v96, v96, v97
	ds_read_b64_tr_b16 v[230:231], v246 offset:20480
	ds_read_b64_tr_b16 v[232:233], v246 offset:22528
	s_waitcnt lgkmcnt(14)
	v_mfma_f32_32x32x16_bf16 v[48:63], v[234:237], v[116:119], v[48:63]
	v_exp_f32_e32 v98, v98
	v_exp_f32_e32 v99, v99
	v_add_f32_e32 v0, v0, v98
	v_add_f32_e32 v15, v15, v99
	v_cvt_pk_bf16_f32 v97, v98, v99
	ds_read_b64_tr_b16 v[234:235], v247 offset:20480
	ds_read_b64_tr_b16 v[236:237], v247 offset:22528
	s_waitcnt lgkmcnt(14)
	v_mfma_f32_32x32x16_bf16 v[32:47], v[238:241], v[116:119], v[32:47]
	v_exp_f32_e32 v100, v100
	v_exp_f32_e32 v101, v101
	v_add_f32_e32 v0, v0, v100
	v_add_f32_e32 v15, v15, v101
	v_cvt_pk_bf16_f32 v98, v100, v101
	ds_read_b64_tr_b16 v[238:239], v248 offset:20480
	ds_read_b64_tr_b16 v[240:241], v248 offset:22528
	s_waitcnt lgkmcnt(14)
	v_mfma_f32_32x32x16_bf16 v[16:31], v[242:245], v[116:119], v[16:31]
	v_exp_f32_e32 v102, v102
	v_exp_f32_e32 v103, v103
	v_add_f32_e32 v0, v0, v102
	v_add_f32_e32 v15, v15, v103
	v_cvt_pk_bf16_f32 v99, v102, v103
	ds_read_b64_tr_b16 v[242:243], v249 offset:20480
	ds_read_b64_tr_b16 v[244:245], v249 offset:22528
	s_waitcnt lgkmcnt(14)
	v_mfma_f32_32x32x16_bf16 v[64:79], v[2:5], v[96:99], v[64:79]
	v_exp_f32_e32 v104, v104
	v_exp_f32_e32 v105, v105
	v_add_f32_e32 v0, v0, v104
	v_add_f32_e32 v15, v15, v105
	v_cvt_pk_bf16_f32 v100, v104, v105
	s_waitcnt lgkmcnt(12)
	v_mfma_f32_32x32x16_bf16 v[48:63], v[6:9], v[96:99], v[48:63]
	v_exp_f32_e32 v106, v106
	v_exp_f32_e32 v107, v107
	v_add_f32_e32 v0, v0, v106
	v_add_f32_e32 v15, v15, v107
	v_cvt_pk_bf16_f32 v101, v106, v107
	s_waitcnt lgkmcnt(10)
	v_mfma_f32_32x32x16_bf16 v[32:47], v[10:13], v[96:99], v[32:47]
	v_exp_f32_e32 v108, v108
	v_exp_f32_e32 v109, v109
	v_add_f32_e32 v0, v0, v108
	v_add_f32_e32 v15, v15, v109
	v_cvt_pk_bf16_f32 v102, v108, v109
	s_waitcnt lgkmcnt(8)
	v_mfma_f32_32x32x16_bf16 v[16:31], v[144:147], v[96:99], v[16:31]
	v_exp_f32_e32 v110, v110
	v_exp_f32_e32 v111, v111
	v_add_f32_e32 v0, v0, v110
	v_add_f32_e32 v15, v15, v111
	v_cvt_pk_bf16_f32 v103, v110, v111
	s_nop 1
	s_waitcnt lgkmcnt(6)
	v_mfma_f32_32x32x16_bf16 v[64:79], v[230:233], v[100:103], v[64:79]
	s_waitcnt lgkmcnt(4)
	v_mfma_f32_32x32x16_bf16 v[48:63], v[234:237], v[100:103], v[48:63]
	s_waitcnt lgkmcnt(2)
	v_mfma_f32_32x32x16_bf16 v[32:47], v[238:241], v[100:103], v[32:47]
	s_waitcnt lgkmcnt(0)
	v_mfma_f32_32x32x16_bf16 v[16:31], v[242:245], v[100:103], v[16:31]
	s_setprio 0
	v_add_f32_e32 v0, v0, v15
	v_add_f32_e32 v14, v14, v0
	s_branch .LBB0_101

; DI unsigned cvt_pk_bf16(float lo, float hi) { unsigned r; asm volatile("v_cvt_pk_bf16_f32 %0, %1, %2" : "=v"(r) : "v"(lo), "v"(hi)); return r; }
; template <int DK>
; DI void attn_pass(const AttnSrc& s, const int q0, const float sc, LAS unsigned char* lds, f32x16 (&O)[4]) {
;     ...
; #pragma unroll
;         for (int j = 0; j < 16; ++j) { p0[j] = __builtin_amdgcn_exp2f(p0[j] * sc - mrun); p1[j] = __builtin_amdgcn_exp2f(p1[j] * sc - mrun); rs += p0[j] + p1[j]; }
;       }
;       lrun += rs;
;       bf16x8 pb[4];
;       { u32x4 w;
;         w.x = cvt_pk_bf16(p0[0], p0[1]); w.y = cvt_pk_bf16(p0[2], p0[3]); w.z = cvt_pk_bf16(p0[4], p0[5]); w.w = cvt_pk_bf16(p0[6], p0[7]); pb[0] = __builtin_bit_cast(bf16x8, w);
;         w.x = cvt_pk_bf16(p0[8], p0[9]); w.y = cvt_pk_bf16(p0[10], p0[11]); w.z = cvt_pk_bf16(p0[12], p0[13]); w.w = cvt_pk_bf16(p0[14], p0[15]); pb[1] = __builtin_bit_cast(bf16x8, w);
;         w.x = cvt_pk_bf16(p1[0], p1[1]); w.y = cvt_pk_bf16(p1[2], p1[3]); w.z = cvt_pk_bf16(p1[4], p1[5]); w.w = cvt_pk_bf16(p1[6], p1[7]); pb[2] = __builtin_bit_cast(bf16x8, w);
;         w.x = cvt_pk_bf16(p1[8], p1[9]); w.y = cvt_pk_bf16(p1[10], p1[11]); w.z = cvt_pk_bf16(p1[12], p1[13]); w.w = cvt_pk_bf16(p1[14], p1[15]); pb[3] = __builtin_bit_cast(bf16x8, w); }
; #pragma unroll
;       for (int vt = 0; vt < 4; ++vt) {
;         if (vt + 1 < 4) vload(vt + 1, (vt + 1) & 1);
;         __builtin_amdgcn_s_setprio(1);
; #pragma unroll
;         for (int ks = 0; ks < 4; ++ks) O[vt] = __builtin_amdgcn_mfma_f32_32x32x16_bf16(vf[vt & 1][ks], pb[ks], O[vt], 0, 0, 0);
;         __builtin_amdgcn_s_setprio(0);
;       }
.Ln192_exp:
	v_fma_f32 v82, v82, s61, -v219
	v_fma_f32 v83, v83, s61, -v219
	v_fma_f32 v84, v84, s61, -v219
	v_fma_f32 v85, v85, s61, -v219
	v_fma_f32 v86, v86, s61, -v219
	v_fma_f32 v87, v87, s61, -v219
	v_fma_f32 v88, v88, s61, -v219
	v_fma_f32 v89, v89, s61, -v219
	v_exp_f32_e32 v82, v82
	v_exp_f32_e32 v83, v83
	v_exp_f32_e32 v84, v84
	v_exp_f32_e32 v85, v85
	v_exp_f32_e32 v86, v86
	v_exp_f32_e32 v87, v87
	v_exp_f32_e32 v88, v88
	v_exp_f32_e32 v89, v89
	v_add_f32_e32 v0, v82, v83
	v_add_f32_e32 v238, v84, v85
	v_add_f32_e32 v0, v0, v86
	v_add_f32_e32 v238, v238, v87
	v_add_f32_e32 v0, v0, v88
	v_add_f32_e32 v238, v238, v89
	v_cvt_pk_bf16_f32 v82, v82, v83
	v_cvt_pk_bf16_f32 v83, v84, v85
	v_cvt_pk_bf16_f32 v84, v86, v87
	v_cvt_pk_bf16_f32 v85, v88, v89
	ds_read_b64_tr_b16 v[220:221], v246 offset:28672
	ds_read_b64_tr_b16 v[222:223], v246 offset:30720
	ds_read_b64_tr_b16 v[224:225], v247 offset:28672
	ds_read_b64_tr_b16 v[226:227], v247 offset:30720
	ds_read_b64_tr_b16 v[230:231], v248 offset:28672
	ds_read_b64_tr_b16 v[232:233], v248 offset:30720
	ds_read_b64_tr_b16 v[234:235], v249 offset:28672
	ds_read_b64_tr_b16 v[236:237], v249 offset:30720
	s_setprio 1
	s_waitcnt lgkmcnt(14)
	v_mfma_f32_32x32x16_bf16 v[50:65], v[146:149], v[82:85], v[50:65]
	v_fma_f32 v90, v90, s61, -v219
	v_fma_f32 v91, v91, s61, -v219
	v_exp_f32_e32 v90, v90
	v_exp_f32_e32 v91, v91
	v_add_f32_e32 v0, v0, v90
	v_add_f32_e32 v238, v238, v91
	v_cvt_pk_bf16_f32 v86, v90, v91
	ds_read_b64_tr_b16 v[146:147], v246 offset:32768
	ds_read_b64_tr_b16 v[148:149], v246 offset:34816
	s_waitcnt lgkmcnt(14)
	v_mfma_f32_32x32x16_bf16 v[34:49], v[150:153], v[82:85], v[34:49]
	v_fma_f32 v92, v92, s61, -v219
	v_fma_f32 v93, v93, s61, -v219
	v_exp_f32_e32 v92, v92
	v_exp_f32_e32 v93, v93
	v_add_f32_e32 v0, v0, v92
	v_add_f32_e32 v238, v238, v93
	v_cvt_pk_bf16_f32 v87, v92, v93
	ds_read_b64_tr_b16 v[150:151], v247 offset:32768
	ds_read_b64_tr_b16 v[152:153], v247 offset:34816
	s_waitcnt lgkmcnt(14)
	v_mfma_f32_32x32x16_bf16 v[18:33], v[154:157], v[82:85], v[18:33]
	v_fma_f32 v94, v94, s61, -v219
	v_fma_f32 v95, v95, s61, -v219
	v_exp_f32_e32 v94, v94
	v_exp_f32_e32 v95, v95
	v_add_f32_e32 v0, v0, v94
	v_add_f32_e32 v238, v238, v95
	v_cvt_pk_bf16_f32 v88, v94, v95
	ds_read_b64_tr_b16 v[154:155], v248 offset:32768
	ds_read_b64_tr_b16 v[156:157], v248 offset:34816
	s_waitcnt lgkmcnt(14)
	v_mfma_f32_32x32x16_bf16 v[2:17], v[158:161], v[82:85], v[2:17]
	v_fma_f32 v96, v96, s61, -v219
	v_fma_f32 v97, v97, s61, -v219
	v_exp_f32_e32 v96, v96
	v_exp_f32_e32 v97, v97
	v_add_f32_e32 v0, v0, v96
	v_add_f32_e32 v238, v238, v97
	v_cvt_pk_bf16_f32 v89, v96, v97
	ds_read_b64_tr_b16 v[158:159], v249 offset:32768
	ds_read_b64_tr_b16 v[160:161], v249 offset:34816
	s_waitcnt lgkmcnt(14)
	v_mfma_f32_32x32x16_bf16 v[50:65], v[220:223], v[86:89], v[50:65]
	v_fma_f32 v66, v66, s61, -v219
	v_fma_f32 v67, v67, s61, -v219
	v_exp_f32_e32 v66, v66
	v_exp_f32_e32 v67, v67
	v_add_f32_e32 v0, v0, v66
	v_add_f32_e32 v238, v238, v67
	v_cvt_pk_bf16_f32 v66, v66, v67
	ds_read_b64_tr_b16 v[220:221], v246 offset:36864
	ds_read_b64_tr_b16 v[222:223], v246 offset:38912
	s_waitcnt lgkmcnt(14)
	v_mfma_f32_32x32x16_bf16 v[34:49], v[224:227], v[86:89], v[34:49]
	v_fma_f32 v68, v68, s61, -v219
	v_fma_f32 v69, v69, s61, -v219
	v_exp_f32_e32 v68, v68
	v_exp_f32_e32 v69, v69
	v_add_f32_e32 v0, v0, v68
	v_add_f32_e32 v238, v238, v69
	v_cvt_pk_bf16_f32 v67, v68, v69
	ds_read_b64_tr_b16 v[224:225], v247 offset:36864
	ds_read_b64_tr_b16 v[226:227], v247 offset:38912
	s_waitcnt lgkmcnt(14)
	v_mfma_f32_32x32x16_bf16 v[18:33], v[230:233], v[86:89], v[18:33]
	v_fma_f32 v70, v70, s61, -v219
	v_fma_f32 v71, v71, s61, -v219
	v_exp_f32_e32 v70, v70
	v_exp_f32_e32 v71, v71
	v_add_f32_e32 v0, v0, v70
	v_add_f32_e32 v238, v238, v71
	v_cvt_pk_bf16_f32 v68, v70, v71
	ds_read_b64_tr_b16 v[230:231], v248 offset:36864
	ds_read_b64_tr_b16 v[232:233], v248 offset:38912
	s_waitcnt lgkmcnt(14)
	v_mfma_f32_32x32x16_bf16 v[2:17], v[234:237], v[86:89], v[2:17]
	v_fma_f32 v72, v72, s61, -v219
	v_fma_f32 v73, v73, s61, -v219
	v_exp_f32_e32 v72, v72
	v_exp_f32_e32 v73, v73
	v_add_f32_e32 v0, v0, v72
	v_add_f32_e32 v238, v238, v73
	v_cvt_pk_bf16_f32 v69, v72, v73
	ds_read_b64_tr_b16 v[234:235], v249 offset:36864
	ds_read_b64_tr_b16 v[236:237], v249 offset:38912
	s_waitcnt lgkmcnt(14)
	v_mfma_f32_32x32x16_bf16 v[50:65], v[146:149], v[66:69], v[50:65]
	v_fma_f32 v74, v74, s61, -v219
	v_fma_f32 v75, v75, s61, -v219
	v_exp_f32_e32 v74, v74
	v_exp_f32_e32 v75, v75
	v_add_f32_e32 v0, v0, v74
	v_add_f32_e32 v238, v238, v75
	v_cvt_pk_bf16_f32 v70, v74, v75
	s_waitcnt lgkmcnt(12)
	v_mfma_f32_32x32x16_bf16 v[34:49], v[150:153], v[66:69], v[34:49]
	v_fma_f32 v76, v76, s61, -v219
	v_fma_f32 v77, v77, s61, -v219
	v_exp_f32_e32 v76, v76
	v_exp_f32_e32 v77, v77
	v_add_f32_e32 v0, v0, v76
	v_add_f32_e32 v238, v238, v77
	v_cvt_pk_bf16_f32 v71, v76, v77
	s_waitcnt lgkmcnt(10)
	v_mfma_f32_32x32x16_bf16 v[18:33], v[154:157], v[66:69], v[18:33]
	v_fma_f32 v78, v78, s61, -v219
	v_fma_f32 v79, v79, s61, -v219
	v_exp_f32_e32 v78, v78
	v_exp_f32_e32 v79, v79
	v_add_f32_e32 v0, v0, v78
	v_add_f32_e32 v238, v238, v79
	v_cvt_pk_bf16_f32 v72, v78, v79
	s_waitcnt lgkmcnt(8)
	v_mfma_f32_32x32x16_bf16 v[2:17], v[158:161], v[66:69], v[2:17]
	v_fma_f32 v80, v80, s61, -v219
	v_fma_f32 v81, v81, s61, -v219
	v_exp_f32_e32 v80, v80
	v_exp_f32_e32 v81, v81
	v_add_f32_e32 v0, v0, v80
	v_add_f32_e32 v238, v238, v81
	v_cvt_pk_bf16_f32 v73, v80, v81
	s_nop 1
	s_waitcnt lgkmcnt(6)
	v_mfma_f32_32x32x16_bf16 v[50:65], v[220:223], v[70:73], v[50:65]
	s_waitcnt lgkmcnt(4)
	v_mfma_f32_32x32x16_bf16 v[34:49], v[224:227], v[70:73], v[34:49]
	s_waitcnt lgkmcnt(2)
	v_mfma_f32_32x32x16_bf16 v[18:33], v[230:233], v[70:73], v[18:33]
	s_waitcnt lgkmcnt(0)
	v_mfma_f32_32x32x16_bf16 v[2:17], v[234:237], v[70:73], v[2:17]
	s_setprio 0
	v_add_f32_e32 v0, v0, v238
	v_add_f32_e32 v218, v218, v0
	s_branch .LBB0_137
